# P11 epilogue: plain (write-back) out stores instead of nt so L2 merges the two 16-byte halves of each line
# speedup vs baseline: 1.0149x; 1.0149x over previous
.LBB0_809:
	s_and_b64 vcc, exec, s[0:1]
	s_mov_b64 s[0:1], -1
	s_ashr_i32 s26, s51, 31
	s_lshr_b32 s26, s26, 27
	s_add_i32 s26, s51, s26
	s_ashr_i32 s26, s26, 5
	s_mul_hi_i32 s27, s26, 0x6000
	s_mulk_i32 s26, 0x6000
	s_add_u32 s26, s42, s26
	s_addc_u32 s27, s43, s27
	v_lshl_add_u32 v156, s51, 8, v158
	v_lshl_or_b32 v252, s52, 8, v160
	v_lshlrev_b32_e32 v156, 11, v156
	v_lshl_add_u32 v156, v252, 1, v156
	v_lshlrev_b32_e32 v157, 1, v156
	v_lshlrev_b32_e32 v252, 2, v252
	global_load_dwordx4 v[228:231], v252, s[26:27]
	global_load_dwordx4 v[232:235], v252, s[26:27] offset:16
	global_load_dwordx4 v[236:239], v252, s[26:27] offset:512
	global_load_dwordx4 v[240:243], v252, s[26:27] offset:528
	global_load_dwordx4 v[244:247], v252, s[8:9]
	global_load_dwordx4 v[248:251], v252, s[8:9] offset:16
	global_load_dwordx4 v[144:147], v252, s[8:9] offset:512
	global_load_dwordx4 v[148:151], v252, s[8:9] offset:528
	s_mov_b32 s16, s14
	s_mov_b32 s17, s15
	global_load_dwordx4 v[164:167], v156, s[16:17] nt
	global_load_dwordx4 v[168:171], v156, s[16:17] offset:256 nt
	s_add_u32 s16, s16, 0x8000
	s_addc_u32 s17, s17, 0
	global_load_dwordx4 v[172:175], v156, s[16:17] nt
	global_load_dwordx4 v[176:179], v156, s[16:17] offset:256 nt
	s_add_u32 s16, s16, 0x8000
	s_addc_u32 s17, s17, 0
	global_load_dwordx4 v[180:183], v156, s[16:17] nt
	global_load_dwordx4 v[184:187], v156, s[16:17] offset:256 nt
	s_add_u32 s16, s16, 0x8000
	s_addc_u32 s17, s17, 0
	global_load_dwordx4 v[188:191], v156, s[16:17] nt
	global_load_dwordx4 v[192:195], v156, s[16:17] offset:256 nt
	s_add_u32 s16, s16, 0x28000
	s_addc_u32 s17, s17, 0
	global_load_dwordx4 v[196:199], v156, s[16:17] nt
	global_load_dwordx4 v[200:203], v156, s[16:17] offset:256 nt
	s_add_u32 s16, s16, 0x8000
	s_addc_u32 s17, s17, 0
	global_load_dwordx4 v[204:207], v156, s[16:17] nt
	global_load_dwordx4 v[208:211], v156, s[16:17] offset:256 nt
	s_add_u32 s16, s16, 0x8000
	s_addc_u32 s17, s17, 0
	global_load_dwordx4 v[212:215], v156, s[16:17] nt
	global_load_dwordx4 v[216:219], v156, s[16:17] offset:256 nt
	s_add_u32 s16, s16, 0x8000
	s_addc_u32 s17, s17, 0
	global_load_dwordx4 v[220:223], v156, s[16:17] nt
	global_load_dwordx4 v[224:227], v156, s[16:17] offset:256 nt
	s_mov_b32 s18, s86
	s_mov_b32 s19, s87
	s_waitcnt vmcnt(16)
	v_pk_add_f32 v[228:229], v[228:229], v[244:245]
	v_pk_add_f32 v[230:231], v[230:231], v[246:247]
	v_pk_add_f32 v[232:233], v[232:233], v[248:249]
	v_pk_add_f32 v[234:235], v[234:235], v[250:251]
	v_pk_add_f32 v[236:237], v[236:237], v[144:145]
	v_pk_add_f32 v[238:239], v[238:239], v[146:147]
	v_pk_add_f32 v[240:241], v[240:241], v[148:149]
	v_pk_add_f32 v[242:243], v[242:243], v[150:151]
	s_waitcnt vmcnt(15)
	v_lshlrev_b32_e32 v152, 16, v164
	v_and_b32_e32 v153, 0xffff0000, v164
	v_pk_fma_f32 v[124:125], v[124:125], v[228:229], v[152:153]
	v_lshlrev_b32_e32 v154, 16, v165
	v_and_b32_e32 v155, 0xffff0000, v165
	v_pk_fma_f32 v[126:127], v[126:127], v[230:231], v[154:155]
	v_lshlrev_b32_e32 v152, 16, v166
	v_and_b32_e32 v153, 0xffff0000, v166
	v_pk_fma_f32 v[120:121], v[120:121], v[232:233], v[152:153]
	v_lshlrev_b32_e32 v154, 16, v167
	v_and_b32_e32 v155, 0xffff0000, v167
	v_pk_fma_f32 v[122:123], v[122:123], v[234:235], v[154:155]
	global_store_dwordx4 v157, v[124:127], s[18:19]
	global_store_dwordx4 v157, v[120:123], s[18:19] offset:16
	s_waitcnt vmcnt(16)
	v_lshlrev_b32_e32 v152, 16, v168
	v_and_b32_e32 v153, 0xffff0000, v168
	v_pk_fma_f32 v[116:117], v[116:117], v[236:237], v[152:153]
	v_lshlrev_b32_e32 v154, 16, v169
	v_and_b32_e32 v155, 0xffff0000, v169
	v_pk_fma_f32 v[118:119], v[118:119], v[238:239], v[154:155]
	v_lshlrev_b32_e32 v152, 16, v170
	v_and_b32_e32 v153, 0xffff0000, v170
	v_pk_fma_f32 v[112:113], v[112:113], v[240:241], v[152:153]
	v_lshlrev_b32_e32 v154, 16, v171
	v_and_b32_e32 v155, 0xffff0000, v171
	v_pk_fma_f32 v[114:115], v[114:115], v[242:243], v[154:155]
	global_store_dwordx4 v157, v[116:119], s[18:19] offset:512
	global_store_dwordx4 v157, v[112:115], s[18:19] offset:528
	s_add_u32 s18, s18, 0x10000
	s_addc_u32 s19, s19, 0
	s_waitcnt vmcnt(17)
	v_lshlrev_b32_e32 v152, 16, v172
	v_and_b32_e32 v153, 0xffff0000, v172
	v_pk_fma_f32 v[108:109], v[108:109], v[228:229], v[152:153]
	v_lshlrev_b32_e32 v154, 16, v173
	v_and_b32_e32 v155, 0xffff0000, v173
	v_pk_fma_f32 v[110:111], v[110:111], v[230:231], v[154:155]
	v_lshlrev_b32_e32 v152, 16, v174
	v_and_b32_e32 v153, 0xffff0000, v174
	v_pk_fma_f32 v[104:105], v[104:105], v[232:233], v[152:153]
	v_lshlrev_b32_e32 v154, 16, v175
	v_and_b32_e32 v155, 0xffff0000, v175
	v_pk_fma_f32 v[106:107], v[106:107], v[234:235], v[154:155]
	global_store_dwordx4 v157, v[108:111], s[18:19]
	global_store_dwordx4 v157, v[104:107], s[18:19] offset:16
	s_waitcnt vmcnt(18)
	v_lshlrev_b32_e32 v152, 16, v176
	v_and_b32_e32 v153, 0xffff0000, v176
	v_pk_fma_f32 v[100:101], v[100:101], v[236:237], v[152:153]
	v_lshlrev_b32_e32 v154, 16, v177
	v_and_b32_e32 v155, 0xffff0000, v177
	v_pk_fma_f32 v[102:103], v[102:103], v[238:239], v[154:155]
	v_lshlrev_b32_e32 v152, 16, v178
	v_and_b32_e32 v153, 0xffff0000, v178
	v_pk_fma_f32 v[96:97], v[96:97], v[240:241], v[152:153]
	v_lshlrev_b32_e32 v154, 16, v179
	v_and_b32_e32 v155, 0xffff0000, v179
	v_pk_fma_f32 v[98:99], v[98:99], v[242:243], v[154:155]
	global_store_dwordx4 v157, v[100:103], s[18:19] offset:512
	global_store_dwordx4 v157, v[96:99], s[18:19] offset:528
	s_add_u32 s18, s18, 0x10000
	s_addc_u32 s19, s19, 0
	s_waitcnt vmcnt(19)
	v_lshlrev_b32_e32 v152, 16, v180
	v_and_b32_e32 v153, 0xffff0000, v180
	v_pk_fma_f32 v[92:93], v[92:93], v[228:229], v[152:153]
	v_lshlrev_b32_e32 v154, 16, v181
	v_and_b32_e32 v155, 0xffff0000, v181
	v_pk_fma_f32 v[94:95], v[94:95], v[230:231], v[154:155]
	v_lshlrev_b32_e32 v152, 16, v182
	v_and_b32_e32 v153, 0xffff0000, v182
	v_pk_fma_f32 v[88:89], v[88:89], v[232:233], v[152:153]
	v_lshlrev_b32_e32 v154, 16, v183
	v_and_b32_e32 v155, 0xffff0000, v183
	v_pk_fma_f32 v[90:91], v[90:91], v[234:235], v[154:155]
	global_store_dwordx4 v157, v[92:95], s[18:19]
	global_store_dwordx4 v157, v[88:91], s[18:19] offset:16
	s_waitcnt vmcnt(20)
	v_lshlrev_b32_e32 v152, 16, v184
	v_and_b32_e32 v153, 0xffff0000, v184
	v_pk_fma_f32 v[84:85], v[84:85], v[236:237], v[152:153]
	v_lshlrev_b32_e32 v154, 16, v185
	v_and_b32_e32 v155, 0xffff0000, v185
	v_pk_fma_f32 v[86:87], v[86:87], v[238:239], v[154:155]
	v_lshlrev_b32_e32 v152, 16, v186
	v_and_b32_e32 v153, 0xffff0000, v186
	v_pk_fma_f32 v[80:81], v[80:81], v[240:241], v[152:153]
	v_lshlrev_b32_e32 v154, 16, v187
	v_and_b32_e32 v155, 0xffff0000, v187
	v_pk_fma_f32 v[82:83], v[82:83], v[242:243], v[154:155]
	global_store_dwordx4 v157, v[84:87], s[18:19] offset:512
	global_store_dwordx4 v157, v[80:83], s[18:19] offset:528
	s_add_u32 s18, s18, 0x10000
	s_addc_u32 s19, s19, 0
	s_waitcnt vmcnt(21)
	v_lshlrev_b32_e32 v152, 16, v188
	v_and_b32_e32 v153, 0xffff0000, v188
	v_pk_fma_f32 v[76:77], v[76:77], v[228:229], v[152:153]
	v_lshlrev_b32_e32 v154, 16, v189
	v_and_b32_e32 v155, 0xffff0000, v189
	v_pk_fma_f32 v[78:79], v[78:79], v[230:231], v[154:155]
	v_lshlrev_b32_e32 v152, 16, v190
	v_and_b32_e32 v153, 0xffff0000, v190
	v_pk_fma_f32 v[72:73], v[72:73], v[232:233], v[152:153]
	v_lshlrev_b32_e32 v154, 16, v191
	v_and_b32_e32 v155, 0xffff0000, v191
	v_pk_fma_f32 v[74:75], v[74:75], v[234:235], v[154:155]
	global_store_dwordx4 v157, v[76:79], s[18:19]
	global_store_dwordx4 v157, v[72:75], s[18:19] offset:16
	s_waitcnt vmcnt(22)
	v_lshlrev_b32_e32 v152, 16, v192
	v_and_b32_e32 v153, 0xffff0000, v192
	v_pk_fma_f32 v[68:69], v[68:69], v[236:237], v[152:153]
	v_lshlrev_b32_e32 v154, 16, v193
	v_and_b32_e32 v155, 0xffff0000, v193
	v_pk_fma_f32 v[70:71], v[70:71], v[238:239], v[154:155]
	v_lshlrev_b32_e32 v152, 16, v194
	v_and_b32_e32 v153, 0xffff0000, v194
	v_pk_fma_f32 v[64:65], v[64:65], v[240:241], v[152:153]
	v_lshlrev_b32_e32 v154, 16, v195
	v_and_b32_e32 v155, 0xffff0000, v195
	v_pk_fma_f32 v[66:67], v[66:67], v[242:243], v[154:155]
	global_store_dwordx4 v157, v[68:71], s[18:19] offset:512
	global_store_dwordx4 v157, v[64:67], s[18:19] offset:528
	s_add_u32 s18, s18, 0x50000
	s_addc_u32 s19, s19, 0
	s_waitcnt vmcnt(23)
	v_lshlrev_b32_e32 v152, 16, v196
	v_and_b32_e32 v153, 0xffff0000, v196
	v_pk_fma_f32 v[60:61], v[60:61], v[228:229], v[152:153]
	v_lshlrev_b32_e32 v154, 16, v197
	v_and_b32_e32 v155, 0xffff0000, v197
	v_pk_fma_f32 v[62:63], v[62:63], v[230:231], v[154:155]
	v_lshlrev_b32_e32 v152, 16, v198
	v_and_b32_e32 v153, 0xffff0000, v198
	v_pk_fma_f32 v[56:57], v[56:57], v[232:233], v[152:153]
	v_lshlrev_b32_e32 v154, 16, v199
	v_and_b32_e32 v155, 0xffff0000, v199
	v_pk_fma_f32 v[58:59], v[58:59], v[234:235], v[154:155]
	global_store_dwordx4 v157, v[60:63], s[18:19]
	global_store_dwordx4 v157, v[56:59], s[18:19] offset:16
	s_waitcnt vmcnt(24)
	v_lshlrev_b32_e32 v152, 16, v200
	v_and_b32_e32 v153, 0xffff0000, v200
	v_pk_fma_f32 v[52:53], v[52:53], v[236:237], v[152:153]
	v_lshlrev_b32_e32 v154, 16, v201
	v_and_b32_e32 v155, 0xffff0000, v201
	v_pk_fma_f32 v[54:55], v[54:55], v[238:239], v[154:155]
	v_lshlrev_b32_e32 v152, 16, v202
	v_and_b32_e32 v153, 0xffff0000, v202
	v_pk_fma_f32 v[48:49], v[48:49], v[240:241], v[152:153]
	v_lshlrev_b32_e32 v154, 16, v203
	v_and_b32_e32 v155, 0xffff0000, v203
	v_pk_fma_f32 v[50:51], v[50:51], v[242:243], v[154:155]
	global_store_dwordx4 v157, v[52:55], s[18:19] offset:512
	global_store_dwordx4 v157, v[48:51], s[18:19] offset:528
	s_add_u32 s18, s18, 0x10000
	s_addc_u32 s19, s19, 0
	s_waitcnt vmcnt(25)
	v_lshlrev_b32_e32 v152, 16, v204
	v_and_b32_e32 v153, 0xffff0000, v204
	v_pk_fma_f32 v[44:45], v[44:45], v[228:229], v[152:153]
	v_lshlrev_b32_e32 v154, 16, v205
	v_and_b32_e32 v155, 0xffff0000, v205
	v_pk_fma_f32 v[46:47], v[46:47], v[230:231], v[154:155]
	v_lshlrev_b32_e32 v152, 16, v206
	v_and_b32_e32 v153, 0xffff0000, v206
	v_pk_fma_f32 v[40:41], v[40:41], v[232:233], v[152:153]
	v_lshlrev_b32_e32 v154, 16, v207
	v_and_b32_e32 v155, 0xffff0000, v207
	v_pk_fma_f32 v[42:43], v[42:43], v[234:235], v[154:155]
	global_store_dwordx4 v157, v[44:47], s[18:19]
	global_store_dwordx4 v157, v[40:43], s[18:19] offset:16
	s_waitcnt vmcnt(26)
	v_lshlrev_b32_e32 v152, 16, v208
	v_and_b32_e32 v153, 0xffff0000, v208
	v_pk_fma_f32 v[36:37], v[36:37], v[236:237], v[152:153]
	v_lshlrev_b32_e32 v154, 16, v209
	v_and_b32_e32 v155, 0xffff0000, v209
	v_pk_fma_f32 v[38:39], v[38:39], v[238:239], v[154:155]
	v_lshlrev_b32_e32 v152, 16, v210
	v_and_b32_e32 v153, 0xffff0000, v210
	v_pk_fma_f32 v[32:33], v[32:33], v[240:241], v[152:153]
	v_lshlrev_b32_e32 v154, 16, v211
	v_and_b32_e32 v155, 0xffff0000, v211
	v_pk_fma_f32 v[34:35], v[34:35], v[242:243], v[154:155]
	global_store_dwordx4 v157, v[36:39], s[18:19] offset:512
	global_store_dwordx4 v157, v[32:35], s[18:19] offset:528
	s_add_u32 s18, s18, 0x10000
	s_addc_u32 s19, s19, 0
	s_waitcnt vmcnt(27)
	v_lshlrev_b32_e32 v152, 16, v212
	v_and_b32_e32 v153, 0xffff0000, v212
	v_pk_fma_f32 v[28:29], v[28:29], v[228:229], v[152:153]
	v_lshlrev_b32_e32 v154, 16, v213
	v_and_b32_e32 v155, 0xffff0000, v213
	v_pk_fma_f32 v[30:31], v[30:31], v[230:231], v[154:155]
	v_lshlrev_b32_e32 v152, 16, v214
	v_and_b32_e32 v153, 0xffff0000, v214
	v_pk_fma_f32 v[24:25], v[24:25], v[232:233], v[152:153]
	v_lshlrev_b32_e32 v154, 16, v215
	v_and_b32_e32 v155, 0xffff0000, v215
	v_pk_fma_f32 v[26:27], v[26:27], v[234:235], v[154:155]
	global_store_dwordx4 v157, v[28:31], s[18:19]
	global_store_dwordx4 v157, v[24:27], s[18:19] offset:16
	s_waitcnt vmcnt(28)
	v_lshlrev_b32_e32 v152, 16, v216
	v_and_b32_e32 v153, 0xffff0000, v216
	v_pk_fma_f32 v[20:21], v[20:21], v[236:237], v[152:153]
	v_lshlrev_b32_e32 v154, 16, v217
	v_and_b32_e32 v155, 0xffff0000, v217
	v_pk_fma_f32 v[22:23], v[22:23], v[238:239], v[154:155]
	v_lshlrev_b32_e32 v152, 16, v218
	v_and_b32_e32 v153, 0xffff0000, v218
	v_pk_fma_f32 v[16:17], v[16:17], v[240:241], v[152:153]
	v_lshlrev_b32_e32 v154, 16, v219
	v_and_b32_e32 v155, 0xffff0000, v219
	v_pk_fma_f32 v[18:19], v[18:19], v[242:243], v[154:155]
	global_store_dwordx4 v157, v[20:23], s[18:19] offset:512
	global_store_dwordx4 v157, v[16:19], s[18:19] offset:528
	s_add_u32 s18, s18, 0x10000
	s_addc_u32 s19, s19, 0
	s_waitcnt vmcnt(29)
	v_lshlrev_b32_e32 v152, 16, v220
	v_and_b32_e32 v153, 0xffff0000, v220
	v_pk_fma_f32 v[12:13], v[12:13], v[228:229], v[152:153]
	v_lshlrev_b32_e32 v154, 16, v221
	v_and_b32_e32 v155, 0xffff0000, v221
	v_pk_fma_f32 v[14:15], v[14:15], v[230:231], v[154:155]
	v_lshlrev_b32_e32 v152, 16, v222
	v_and_b32_e32 v153, 0xffff0000, v222
	v_pk_fma_f32 v[8:9], v[8:9], v[232:233], v[152:153]
	v_lshlrev_b32_e32 v154, 16, v223
	v_and_b32_e32 v155, 0xffff0000, v223
	v_pk_fma_f32 v[10:11], v[10:11], v[234:235], v[154:155]
	global_store_dwordx4 v157, v[12:15], s[18:19]
	global_store_dwordx4 v157, v[8:11], s[18:19] offset:16
	s_waitcnt vmcnt(30)
	v_lshlrev_b32_e32 v152, 16, v224
	v_and_b32_e32 v153, 0xffff0000, v224
	v_pk_fma_f32 v[4:5], v[4:5], v[236:237], v[152:153]
	v_lshlrev_b32_e32 v154, 16, v225
	v_and_b32_e32 v155, 0xffff0000, v225
	v_pk_fma_f32 v[6:7], v[6:7], v[238:239], v[154:155]
	v_lshlrev_b32_e32 v152, 16, v226
	v_and_b32_e32 v153, 0xffff0000, v226
	v_pk_fma_f32 v[0:1], v[0:1], v[240:241], v[152:153]
	v_lshlrev_b32_e32 v154, 16, v227
	v_and_b32_e32 v155, 0xffff0000, v227
	v_pk_fma_f32 v[2:3], v[2:3], v[242:243], v[154:155]
	global_store_dwordx4 v157, v[4:7], s[18:19] offset:512
	global_store_dwordx4 v157, v[0:3], s[18:19] offset:528
	s_cbranch_vccnz .LBB0_794
	s_andn2_b64 vcc, exec, s[6:7]
	s_cbranch_vccnz .LBB0_793
	s_barrier
	s_branch .LBB0_793
